# v1 + same-accumulator MFMA pairs issued back-to-back (k0,k1 adjacent)
# speedup vs baseline: 1.0161x; 1.0088x over previous
.LBB0_341:
	s_add_u32 s14, s12, 0xfff00080
	s_addc_u32 s15, s13, -1
	s_add_i32 s30, 0, 0x10000
	s_cmp_eq_u32 s39, 60
	s_cselect_b32 s17, s51, s15
	s_cselect_b32 s16, s50, s14
	v_add_u32_e32 v130, s30, v159
	s_cselect_b32 s15, s53, s1
	s_cselect_b32 s14, s52, s0
	s_add_i32 s42, 0, 0x14000
	s_add_i32 m0, s8, 0xc000
	ds_read_b128 v[152:155], v130
	ds_read_b128 v[162:165], v130 offset:1024
	global_load_lds_dwordx4 v148, s[12:13]
	s_add_i32 m0, s8, 0xe000
	ds_read_b128 v[166:169], v130 offset:2048
	ds_read_b128 v[170:173], v130 offset:3072
	global_load_lds_dwordx4 v150, s[12:13]
	v_add_u32_e32 v130, s42, v159
	ds_read_b128 v[174:177], v130
	ds_read_b128 v[182:185], v130 offset:1024
	ds_read_b128 v[186:189], v130 offset:2048
	ds_read_b128 v[190:193], v130 offset:3072
	ds_read_b128 v[194:197], v161
	ds_read_b128 v[198:201], v161 offset:1024
	ds_read_b128 v[202:205], v161 offset:2048
	ds_read_b128 v[206:209], v161 offset:3072
	ds_read_b128 v[210:213], v161 offset:4096
	ds_read_b128 v[214:217], v161 offset:5120
	ds_read_b128 v[218:221], v161 offset:6144
	ds_read_b128 v[222:225], v161 offset:7168
	s_waitcnt vmcnt(8)
	s_waitcnt lgkmcnt(0)
	s_barrier
	s_setprio 1
	s_waitcnt lgkmcnt(0)
	v_mfma_f32_16x16x32_bf16 v[126:129], v[152:155], v[194:197], v[126:129]
	v_mfma_f32_16x16x32_bf16 v[126:129], v[162:165], v[198:201], v[126:129]
	v_mfma_f32_16x16x32_bf16 v[122:125], v[166:169], v[194:197], v[122:125]
	v_mfma_f32_16x16x32_bf16 v[122:125], v[170:173], v[198:201], v[122:125]
	v_mfma_f32_16x16x32_bf16 v[110:113], v[152:155], v[202:205], v[110:113]
	v_mfma_f32_16x16x32_bf16 v[110:113], v[162:165], v[206:209], v[110:113]
	v_mfma_f32_16x16x32_bf16 v[106:109], v[166:169], v[202:205], v[106:109]
	v_mfma_f32_16x16x32_bf16 v[106:109], v[170:173], v[206:209], v[106:109]
	v_mfma_f32_16x16x32_bf16 v[94:97], v[152:155], v[210:213], v[94:97]
	v_mfma_f32_16x16x32_bf16 v[94:97], v[162:165], v[214:217], v[94:97]
	v_mfma_f32_16x16x32_bf16 v[90:93], v[166:169], v[210:213], v[90:93]
	v_mfma_f32_16x16x32_bf16 v[90:93], v[170:173], v[214:217], v[90:93]
	v_mfma_f32_16x16x32_bf16 v[78:81], v[152:155], v[218:221], v[78:81]
	v_mfma_f32_16x16x32_bf16 v[78:81], v[162:165], v[222:225], v[78:81]
	v_mfma_f32_16x16x32_bf16 v[74:77], v[166:169], v[218:221], v[74:77]
	v_mfma_f32_16x16x32_bf16 v[74:77], v[170:173], v[222:225], v[74:77]
	s_setprio 0
	s_setprio 1
	v_mfma_f32_16x16x32_bf16 v[118:121], v[174:177], v[194:197], v[118:121]
	v_mfma_f32_16x16x32_bf16 v[118:121], v[182:185], v[198:201], v[118:121]
	v_mfma_f32_16x16x32_bf16 v[114:117], v[186:189], v[194:197], v[114:117]
	v_mfma_f32_16x16x32_bf16 v[114:117], v[190:193], v[198:201], v[114:117]
	v_mfma_f32_16x16x32_bf16 v[102:105], v[174:177], v[202:205], v[102:105]
	v_mfma_f32_16x16x32_bf16 v[102:105], v[182:185], v[206:209], v[102:105]
	v_mfma_f32_16x16x32_bf16 v[98:101], v[186:189], v[202:205], v[98:101]
	v_mfma_f32_16x16x32_bf16 v[98:101], v[190:193], v[206:209], v[98:101]
	v_mfma_f32_16x16x32_bf16 v[86:89], v[174:177], v[210:213], v[86:89]
	v_mfma_f32_16x16x32_bf16 v[86:89], v[182:185], v[214:217], v[86:89]
	v_mfma_f32_16x16x32_bf16 v[82:85], v[186:189], v[210:213], v[82:85]
	v_mfma_f32_16x16x32_bf16 v[82:85], v[190:193], v[214:217], v[82:85]
	v_mfma_f32_16x16x32_bf16 v[70:73], v[174:177], v[218:221], v[70:73]
	v_mfma_f32_16x16x32_bf16 v[70:73], v[182:185], v[222:225], v[70:73]
	v_mfma_f32_16x16x32_bf16 v[66:69], v[186:189], v[218:221], v[66:69]
	v_mfma_f32_16x16x32_bf16 v[66:69], v[190:193], v[222:225], v[66:69]
	s_setprio 0
	s_barrier
	s_add_i32 m0, s28, 0x10000
	ds_read_b128 v[194:197], v161 offset:16384
	ds_read_b128 v[198:201], v161 offset:17408
	global_load_lds_dwordx4 v144, s[14:15]
	s_add_i32 m0, s28, 0x12000
	s_add_u32 s98, s14, 0x100000
	s_addc_u32 s99, s15, 0
	ds_read_b128 v[202:205], v161 offset:18432
	global_load_lds_dwordx4 v140, s[14:15]
	s_add_i32 m0, s28, 0x14000
	ds_read_b128 v[206:209], v161 offset:19456
	ds_read_b128 v[210:213], v161 offset:20480
	global_load_lds_dwordx4 v144, s[98:99]
	s_add_i32 m0, s28, 0x16000
	ds_read_b128 v[214:217], v161 offset:21504
	ds_read_b128 v[218:221], v161 offset:22528
	global_load_lds_dwordx4 v140, s[98:99]
	s_mov_b32 m0, s8
	ds_read_b128 v[222:225], v161 offset:23552
	global_load_lds_dwordx4 v146, s[16:17]
	s_mov_b32 m0, s9
	s_nop 0
	global_load_lds_dwordx4 v142, s[16:17]
	s_waitcnt vmcnt(8)
	s_waitcnt lgkmcnt(0)
	s_barrier
	s_setprio 1
	s_waitcnt lgkmcnt(0)
	v_mfma_f32_16x16x32_bf16 v[62:65], v[152:155], v[194:197], v[62:65]
	v_mfma_f32_16x16x32_bf16 v[62:65], v[162:165], v[198:201], v[62:65]
	v_mfma_f32_16x16x32_bf16 v[58:61], v[166:169], v[194:197], v[58:61]
	v_mfma_f32_16x16x32_bf16 v[58:61], v[170:173], v[198:201], v[58:61]
	v_mfma_f32_16x16x32_bf16 v[46:49], v[152:155], v[202:205], v[46:49]
	v_mfma_f32_16x16x32_bf16 v[46:49], v[162:165], v[206:209], v[46:49]
	v_mfma_f32_16x16x32_bf16 v[42:45], v[166:169], v[202:205], v[42:45]
	v_mfma_f32_16x16x32_bf16 v[42:45], v[170:173], v[206:209], v[42:45]
	v_mfma_f32_16x16x32_bf16 v[30:33], v[152:155], v[210:213], v[30:33]
	v_mfma_f32_16x16x32_bf16 v[30:33], v[162:165], v[214:217], v[30:33]
	v_mfma_f32_16x16x32_bf16 v[26:29], v[166:169], v[210:213], v[26:29]
	v_mfma_f32_16x16x32_bf16 v[26:29], v[170:173], v[214:217], v[26:29]
	v_mfma_f32_16x16x32_bf16 v[14:17], v[152:155], v[218:221], v[14:17]
	v_mfma_f32_16x16x32_bf16 v[14:17], v[162:165], v[222:225], v[14:17]
	v_mfma_f32_16x16x32_bf16 v[10:13], v[166:169], v[218:221], v[10:13]
	v_mfma_f32_16x16x32_bf16 v[10:13], v[170:173], v[222:225], v[10:13]
	s_setprio 0
	s_setprio 1
	v_mfma_f32_16x16x32_bf16 v[54:57], v[174:177], v[194:197], v[54:57]
	v_mfma_f32_16x16x32_bf16 v[54:57], v[182:185], v[198:201], v[54:57]
	v_mfma_f32_16x16x32_bf16 v[50:53], v[186:189], v[194:197], v[50:53]
	v_mfma_f32_16x16x32_bf16 v[50:53], v[190:193], v[198:201], v[50:53]
	v_mfma_f32_16x16x32_bf16 v[38:41], v[174:177], v[202:205], v[38:41]
	v_mfma_f32_16x16x32_bf16 v[38:41], v[182:185], v[206:209], v[38:41]
	v_mfma_f32_16x16x32_bf16 v[34:37], v[186:189], v[202:205], v[34:37]
	v_mfma_f32_16x16x32_bf16 v[34:37], v[190:193], v[206:209], v[34:37]
	v_mfma_f32_16x16x32_bf16 v[22:25], v[174:177], v[210:213], v[22:25]
	v_mfma_f32_16x16x32_bf16 v[22:25], v[182:185], v[214:217], v[22:25]
	v_mfma_f32_16x16x32_bf16 v[18:21], v[186:189], v[210:213], v[18:21]
	v_mfma_f32_16x16x32_bf16 v[18:21], v[190:193], v[214:217], v[18:21]
	v_mfma_f32_16x16x32_bf16 v[6:9], v[174:177], v[218:221], v[6:9]
	v_mfma_f32_16x16x32_bf16 v[6:9], v[182:185], v[222:225], v[6:9]
	v_mfma_f32_16x16x32_bf16 v[2:5], v[186:189], v[218:221], v[2:5]
	v_mfma_f32_16x16x32_bf16 v[2:5], v[190:193], v[222:225], v[2:5]
	s_setprio 0
	s_barrier
	s_add_u32 s100, s16, 0x100000
	s_addc_u32 s101, s17, 0
	s_mov_b32 m0, s29
	s_add_i32 s30, 0, 0x18000
	v_add_u32_e32 v130, s30, v159
	s_add_i32 s31, 0, 0x1c000
	ds_read_b128 v[152:155], v130
	ds_read_b128 v[162:165], v130 offset:1024
	global_load_lds_dwordx4 v146, s[100:101]
	s_mov_b32 m0, s36
	ds_read_b128 v[166:169], v130 offset:2048
	ds_read_b128 v[170:173], v130 offset:3072
	global_load_lds_dwordx4 v142, s[100:101]
	v_add_u32_e32 v130, s31, v159
	ds_read_b128 v[174:177], v130
	ds_read_b128 v[182:185], v130 offset:1024
	ds_read_b128 v[186:189], v130 offset:2048
	ds_read_b128 v[190:193], v130 offset:3072
	ds_read_b128 v[194:197], v161 offset:32768
	ds_read_b128 v[198:201], v161 offset:33792
	ds_read_b128 v[202:205], v161 offset:34816
	ds_read_b128 v[206:209], v161 offset:35840
	ds_read_b128 v[210:213], v161 offset:36864
	ds_read_b128 v[214:217], v161 offset:37888
	ds_read_b128 v[218:221], v161 offset:38912
	ds_read_b128 v[222:225], v161 offset:39936
	s_waitcnt vmcnt(8)
	s_waitcnt lgkmcnt(0)
	s_barrier
	s_setprio 1
	s_waitcnt lgkmcnt(0)
	v_mfma_f32_16x16x32_bf16 v[126:129], v[152:155], v[194:197], v[126:129]
	v_mfma_f32_16x16x32_bf16 v[126:129], v[162:165], v[198:201], v[126:129]
	v_mfma_f32_16x16x32_bf16 v[122:125], v[166:169], v[194:197], v[122:125]
	v_mfma_f32_16x16x32_bf16 v[122:125], v[170:173], v[198:201], v[122:125]
	v_mfma_f32_16x16x32_bf16 v[110:113], v[152:155], v[202:205], v[110:113]
	v_mfma_f32_16x16x32_bf16 v[110:113], v[162:165], v[206:209], v[110:113]
	v_mfma_f32_16x16x32_bf16 v[106:109], v[166:169], v[202:205], v[106:109]
	v_mfma_f32_16x16x32_bf16 v[106:109], v[170:173], v[206:209], v[106:109]
	v_mfma_f32_16x16x32_bf16 v[94:97], v[152:155], v[210:213], v[94:97]
	v_mfma_f32_16x16x32_bf16 v[94:97], v[162:165], v[214:217], v[94:97]
	v_mfma_f32_16x16x32_bf16 v[90:93], v[166:169], v[210:213], v[90:93]
	v_mfma_f32_16x16x32_bf16 v[90:93], v[170:173], v[214:217], v[90:93]
	v_mfma_f32_16x16x32_bf16 v[78:81], v[152:155], v[218:221], v[78:81]
	v_mfma_f32_16x16x32_bf16 v[78:81], v[162:165], v[222:225], v[78:81]
	v_mfma_f32_16x16x32_bf16 v[74:77], v[166:169], v[218:221], v[74:77]
	v_mfma_f32_16x16x32_bf16 v[74:77], v[170:173], v[222:225], v[74:77]
	s_setprio 0
	s_setprio 1
	v_mfma_f32_16x16x32_bf16 v[118:121], v[174:177], v[194:197], v[118:121]
	v_mfma_f32_16x16x32_bf16 v[118:121], v[182:185], v[198:201], v[118:121]
	v_mfma_f32_16x16x32_bf16 v[114:117], v[186:189], v[194:197], v[114:117]
	v_mfma_f32_16x16x32_bf16 v[114:117], v[190:193], v[198:201], v[114:117]
	v_mfma_f32_16x16x32_bf16 v[102:105], v[174:177], v[202:205], v[102:105]
	v_mfma_f32_16x16x32_bf16 v[102:105], v[182:185], v[206:209], v[102:105]
	v_mfma_f32_16x16x32_bf16 v[98:101], v[186:189], v[202:205], v[98:101]
	v_mfma_f32_16x16x32_bf16 v[98:101], v[190:193], v[206:209], v[98:101]
	v_mfma_f32_16x16x32_bf16 v[86:89], v[174:177], v[210:213], v[86:89]
	v_mfma_f32_16x16x32_bf16 v[86:89], v[182:185], v[214:217], v[86:89]
	v_mfma_f32_16x16x32_bf16 v[82:85], v[186:189], v[210:213], v[82:85]
	v_mfma_f32_16x16x32_bf16 v[82:85], v[190:193], v[214:217], v[82:85]
	v_mfma_f32_16x16x32_bf16 v[70:73], v[174:177], v[218:221], v[70:73]
	v_mfma_f32_16x16x32_bf16 v[70:73], v[182:185], v[222:225], v[70:73]
	v_mfma_f32_16x16x32_bf16 v[66:69], v[186:189], v[218:221], v[66:69]
	v_mfma_f32_16x16x32_bf16 v[66:69], v[190:193], v[222:225], v[66:69]
	s_setprio 0
	s_barrier
	s_add_u32 s14, s14, 0x80
	s_addc_u32 s15, s15, 0
	s_add_i32 m0, s28, 0x18000
	ds_read_b128 v[194:197], v161 offset:49152
	ds_read_b128 v[198:201], v161 offset:50176
	global_load_lds_dwordx4 v144, s[14:15]
	s_add_i32 m0, s28, 0x1a000
	s_add_u32 s98, s98, 0x80
	s_addc_u32 s99, s99, 0
	ds_read_b128 v[202:205], v161 offset:51200
	global_load_lds_dwordx4 v140, s[14:15]
	s_add_i32 m0, s28, 0x1c000
	ds_read_b128 v[206:209], v161 offset:52224
	ds_read_b128 v[210:213], v161 offset:53248
	global_load_lds_dwordx4 v144, s[98:99]
	s_add_i32 m0, s28, 0x1e000
	s_add_u32 s16, s16, 0x80
	s_addc_u32 s17, s17, 0
	ds_read_b128 v[214:217], v161 offset:54272
	ds_read_b128 v[218:221], v161 offset:55296
	global_load_lds_dwordx4 v140, s[98:99]
	s_mov_b32 m0, s45
	ds_read_b128 v[222:225], v161 offset:56320
	global_load_lds_dwordx4 v146, s[16:17]
	s_mov_b32 m0, s46
	s_nop 0
	global_load_lds_dwordx4 v142, s[16:17]
	s_waitcnt vmcnt(8)
	s_waitcnt lgkmcnt(0)
	s_barrier
	s_setprio 1
	s_waitcnt lgkmcnt(0)
	v_mfma_f32_16x16x32_bf16 v[62:65], v[152:155], v[194:197], v[62:65]
	v_mfma_f32_16x16x32_bf16 v[62:65], v[162:165], v[198:201], v[62:65]
	v_mfma_f32_16x16x32_bf16 v[58:61], v[166:169], v[194:197], v[58:61]
	v_mfma_f32_16x16x32_bf16 v[58:61], v[170:173], v[198:201], v[58:61]
	v_mfma_f32_16x16x32_bf16 v[46:49], v[152:155], v[202:205], v[46:49]
	v_mfma_f32_16x16x32_bf16 v[46:49], v[162:165], v[206:209], v[46:49]
	v_mfma_f32_16x16x32_bf16 v[42:45], v[166:169], v[202:205], v[42:45]
	v_mfma_f32_16x16x32_bf16 v[42:45], v[170:173], v[206:209], v[42:45]
	v_mfma_f32_16x16x32_bf16 v[30:33], v[152:155], v[210:213], v[30:33]
	v_mfma_f32_16x16x32_bf16 v[30:33], v[162:165], v[214:217], v[30:33]
	v_mfma_f32_16x16x32_bf16 v[26:29], v[166:169], v[210:213], v[26:29]
	v_mfma_f32_16x16x32_bf16 v[26:29], v[170:173], v[214:217], v[26:29]
	v_mfma_f32_16x16x32_bf16 v[14:17], v[152:155], v[218:221], v[14:17]
	v_mfma_f32_16x16x32_bf16 v[14:17], v[162:165], v[222:225], v[14:17]
	v_mfma_f32_16x16x32_bf16 v[10:13], v[166:169], v[218:221], v[10:13]
	v_mfma_f32_16x16x32_bf16 v[10:13], v[170:173], v[222:225], v[10:13]
	s_setprio 0
	s_setprio 1
	v_mfma_f32_16x16x32_bf16 v[54:57], v[174:177], v[194:197], v[54:57]
	v_mfma_f32_16x16x32_bf16 v[54:57], v[182:185], v[198:201], v[54:57]
	v_mfma_f32_16x16x32_bf16 v[50:53], v[186:189], v[194:197], v[50:53]
	v_mfma_f32_16x16x32_bf16 v[50:53], v[190:193], v[198:201], v[50:53]
	v_mfma_f32_16x16x32_bf16 v[38:41], v[174:177], v[202:205], v[38:41]
	v_mfma_f32_16x16x32_bf16 v[38:41], v[182:185], v[206:209], v[38:41]
	v_mfma_f32_16x16x32_bf16 v[34:37], v[186:189], v[202:205], v[34:37]
	v_mfma_f32_16x16x32_bf16 v[34:37], v[190:193], v[206:209], v[34:37]
	v_mfma_f32_16x16x32_bf16 v[22:25], v[174:177], v[210:213], v[22:25]
	v_mfma_f32_16x16x32_bf16 v[22:25], v[182:185], v[214:217], v[22:25]
	v_mfma_f32_16x16x32_bf16 v[18:21], v[186:189], v[210:213], v[18:21]
	v_mfma_f32_16x16x32_bf16 v[18:21], v[190:193], v[214:217], v[18:21]
	v_mfma_f32_16x16x32_bf16 v[6:9], v[174:177], v[218:221], v[6:9]
	v_mfma_f32_16x16x32_bf16 v[6:9], v[182:185], v[222:225], v[6:9]
	v_mfma_f32_16x16x32_bf16 v[2:5], v[186:189], v[218:221], v[2:5]
	v_mfma_f32_16x16x32_bf16 v[2:5], v[190:193], v[222:225], v[2:5]
	s_setprio 0
	s_barrier
	s_add_i32 s39, s39, 2
	s_add_u32 s12, s12, 0x100
	s_addc_u32 s13, s13, 0
	s_add_u32 s0, s0, 0x100
	s_addc_u32 s1, s1, 0
	s_cmp_gt_u32 s39, 61
	s_cbranch_scc0 .LBB0_341
	s_and_b64 vcc, exec, s[34:35]
	s_cbranch_vccz .LBB0_344
	s_barrier

.LBB0_572:
	s_add_u32 s14, s12, 0xfff00080
	s_addc_u32 s15, s13, -1
	s_add_i32 s30, 0, 0x10000
	s_cmp_eq_u32 s35, 60
	s_cselect_b32 s17, s51, s15
	s_cselect_b32 s16, s50, s14
	v_add_u32_e32 v130, s30, v159
	s_cselect_b32 s15, s53, s1
	s_cselect_b32 s14, s52, s0
	s_add_i32 s42, 0, 0x14000
	s_add_i32 m0, s8, 0xc000
	ds_read_b128 v[152:155], v130
	ds_read_b128 v[162:165], v130 offset:1024
	global_load_lds_dwordx4 v148, s[12:13]
	s_add_i32 m0, s8, 0xe000
	ds_read_b128 v[166:169], v130 offset:2048
	ds_read_b128 v[170:173], v130 offset:3072
	global_load_lds_dwordx4 v150, s[12:13]
	v_add_u32_e32 v130, s42, v159
	ds_read_b128 v[174:177], v130
	ds_read_b128 v[182:185], v130 offset:1024
	ds_read_b128 v[186:189], v130 offset:2048
	ds_read_b128 v[190:193], v130 offset:3072
	ds_read_b128 v[194:197], v161
	ds_read_b128 v[198:201], v161 offset:1024
	ds_read_b128 v[202:205], v161 offset:2048
	ds_read_b128 v[206:209], v161 offset:3072
	ds_read_b128 v[210:213], v161 offset:4096
	ds_read_b128 v[214:217], v161 offset:5120
	ds_read_b128 v[218:221], v161 offset:6144
	ds_read_b128 v[222:225], v161 offset:7168
	s_waitcnt vmcnt(8)
	s_waitcnt lgkmcnt(0)
	s_barrier
	s_setprio 1
	s_waitcnt lgkmcnt(0)
	v_mfma_f32_16x16x32_bf16 v[126:129], v[152:155], v[194:197], v[126:129]
	v_mfma_f32_16x16x32_bf16 v[126:129], v[162:165], v[198:201], v[126:129]
	v_mfma_f32_16x16x32_bf16 v[122:125], v[166:169], v[194:197], v[122:125]
	v_mfma_f32_16x16x32_bf16 v[122:125], v[170:173], v[198:201], v[122:125]
	v_mfma_f32_16x16x32_bf16 v[110:113], v[152:155], v[202:205], v[110:113]
	v_mfma_f32_16x16x32_bf16 v[110:113], v[162:165], v[206:209], v[110:113]
	v_mfma_f32_16x16x32_bf16 v[106:109], v[166:169], v[202:205], v[106:109]
	v_mfma_f32_16x16x32_bf16 v[106:109], v[170:173], v[206:209], v[106:109]
	v_mfma_f32_16x16x32_bf16 v[94:97], v[152:155], v[210:213], v[94:97]
	v_mfma_f32_16x16x32_bf16 v[94:97], v[162:165], v[214:217], v[94:97]
	v_mfma_f32_16x16x32_bf16 v[90:93], v[166:169], v[210:213], v[90:93]
	v_mfma_f32_16x16x32_bf16 v[90:93], v[170:173], v[214:217], v[90:93]
	v_mfma_f32_16x16x32_bf16 v[78:81], v[152:155], v[218:221], v[78:81]
	v_mfma_f32_16x16x32_bf16 v[78:81], v[162:165], v[222:225], v[78:81]
	v_mfma_f32_16x16x32_bf16 v[74:77], v[166:169], v[218:221], v[74:77]
	v_mfma_f32_16x16x32_bf16 v[74:77], v[170:173], v[222:225], v[74:77]
	s_setprio 0
	s_setprio 1
	v_mfma_f32_16x16x32_bf16 v[118:121], v[174:177], v[194:197], v[118:121]
	v_mfma_f32_16x16x32_bf16 v[118:121], v[182:185], v[198:201], v[118:121]
	v_mfma_f32_16x16x32_bf16 v[114:117], v[186:189], v[194:197], v[114:117]
	v_mfma_f32_16x16x32_bf16 v[114:117], v[190:193], v[198:201], v[114:117]
	v_mfma_f32_16x16x32_bf16 v[102:105], v[174:177], v[202:205], v[102:105]
	v_mfma_f32_16x16x32_bf16 v[102:105], v[182:185], v[206:209], v[102:105]
	v_mfma_f32_16x16x32_bf16 v[98:101], v[186:189], v[202:205], v[98:101]
	v_mfma_f32_16x16x32_bf16 v[98:101], v[190:193], v[206:209], v[98:101]
	v_mfma_f32_16x16x32_bf16 v[86:89], v[174:177], v[210:213], v[86:89]
	v_mfma_f32_16x16x32_bf16 v[86:89], v[182:185], v[214:217], v[86:89]
	v_mfma_f32_16x16x32_bf16 v[82:85], v[186:189], v[210:213], v[82:85]
	v_mfma_f32_16x16x32_bf16 v[82:85], v[190:193], v[214:217], v[82:85]
	v_mfma_f32_16x16x32_bf16 v[70:73], v[174:177], v[218:221], v[70:73]
	v_mfma_f32_16x16x32_bf16 v[70:73], v[182:185], v[222:225], v[70:73]
	v_mfma_f32_16x16x32_bf16 v[66:69], v[186:189], v[218:221], v[66:69]
	v_mfma_f32_16x16x32_bf16 v[66:69], v[190:193], v[222:225], v[66:69]
	s_setprio 0
	s_barrier
	s_add_i32 m0, s28, 0x10000
	ds_read_b128 v[194:197], v161 offset:16384
	ds_read_b128 v[198:201], v161 offset:17408
	global_load_lds_dwordx4 v144, s[14:15]
	s_add_i32 m0, s28, 0x12000
	s_add_u32 s98, s14, 0x100000
	s_addc_u32 s99, s15, 0
	ds_read_b128 v[202:205], v161 offset:18432
	global_load_lds_dwordx4 v140, s[14:15]
	s_add_i32 m0, s28, 0x14000
	ds_read_b128 v[206:209], v161 offset:19456
	ds_read_b128 v[210:213], v161 offset:20480
	global_load_lds_dwordx4 v144, s[98:99]
	s_add_i32 m0, s28, 0x16000
	ds_read_b128 v[214:217], v161 offset:21504
	ds_read_b128 v[218:221], v161 offset:22528
	global_load_lds_dwordx4 v140, s[98:99]
	s_mov_b32 m0, s8
	ds_read_b128 v[222:225], v161 offset:23552
	global_load_lds_dwordx4 v146, s[16:17]
	s_mov_b32 m0, s9
	s_nop 0
	global_load_lds_dwordx4 v142, s[16:17]
	s_waitcnt vmcnt(8)
	s_waitcnt lgkmcnt(0)
	s_barrier
	s_setprio 1
	s_waitcnt lgkmcnt(0)
	v_mfma_f32_16x16x32_bf16 v[62:65], v[152:155], v[194:197], v[62:65]
	v_mfma_f32_16x16x32_bf16 v[62:65], v[162:165], v[198:201], v[62:65]
	v_mfma_f32_16x16x32_bf16 v[58:61], v[166:169], v[194:197], v[58:61]
	v_mfma_f32_16x16x32_bf16 v[58:61], v[170:173], v[198:201], v[58:61]
	v_mfma_f32_16x16x32_bf16 v[46:49], v[152:155], v[202:205], v[46:49]
	v_mfma_f32_16x16x32_bf16 v[46:49], v[162:165], v[206:209], v[46:49]
	v_mfma_f32_16x16x32_bf16 v[42:45], v[166:169], v[202:205], v[42:45]
	v_mfma_f32_16x16x32_bf16 v[42:45], v[170:173], v[206:209], v[42:45]
	v_mfma_f32_16x16x32_bf16 v[30:33], v[152:155], v[210:213], v[30:33]
	v_mfma_f32_16x16x32_bf16 v[30:33], v[162:165], v[214:217], v[30:33]
	v_mfma_f32_16x16x32_bf16 v[26:29], v[166:169], v[210:213], v[26:29]
	v_mfma_f32_16x16x32_bf16 v[26:29], v[170:173], v[214:217], v[26:29]
	v_mfma_f32_16x16x32_bf16 v[14:17], v[152:155], v[218:221], v[14:17]
	v_mfma_f32_16x16x32_bf16 v[14:17], v[162:165], v[222:225], v[14:17]
	v_mfma_f32_16x16x32_bf16 v[10:13], v[166:169], v[218:221], v[10:13]
	v_mfma_f32_16x16x32_bf16 v[10:13], v[170:173], v[222:225], v[10:13]
	s_setprio 0
	s_setprio 1
	v_mfma_f32_16x16x32_bf16 v[54:57], v[174:177], v[194:197], v[54:57]
	v_mfma_f32_16x16x32_bf16 v[54:57], v[182:185], v[198:201], v[54:57]
	v_mfma_f32_16x16x32_bf16 v[50:53], v[186:189], v[194:197], v[50:53]
	v_mfma_f32_16x16x32_bf16 v[50:53], v[190:193], v[198:201], v[50:53]
	v_mfma_f32_16x16x32_bf16 v[38:41], v[174:177], v[202:205], v[38:41]
	v_mfma_f32_16x16x32_bf16 v[38:41], v[182:185], v[206:209], v[38:41]
	v_mfma_f32_16x16x32_bf16 v[34:37], v[186:189], v[202:205], v[34:37]
	v_mfma_f32_16x16x32_bf16 v[34:37], v[190:193], v[206:209], v[34:37]
	v_mfma_f32_16x16x32_bf16 v[22:25], v[174:177], v[210:213], v[22:25]
	v_mfma_f32_16x16x32_bf16 v[22:25], v[182:185], v[214:217], v[22:25]
	v_mfma_f32_16x16x32_bf16 v[18:21], v[186:189], v[210:213], v[18:21]
	v_mfma_f32_16x16x32_bf16 v[18:21], v[190:193], v[214:217], v[18:21]
	v_mfma_f32_16x16x32_bf16 v[6:9], v[174:177], v[218:221], v[6:9]
	v_mfma_f32_16x16x32_bf16 v[6:9], v[182:185], v[222:225], v[6:9]
	v_mfma_f32_16x16x32_bf16 v[2:5], v[186:189], v[218:221], v[2:5]
	v_mfma_f32_16x16x32_bf16 v[2:5], v[190:193], v[222:225], v[2:5]
	s_setprio 0
	s_barrier
	s_add_u32 s100, s16, 0x100000
	s_addc_u32 s101, s17, 0
	s_mov_b32 m0, s29
	s_add_i32 s30, 0, 0x18000
	v_add_u32_e32 v130, s30, v159
	s_add_i32 s31, 0, 0x1c000
	ds_read_b128 v[152:155], v130
	ds_read_b128 v[162:165], v130 offset:1024
	global_load_lds_dwordx4 v146, s[100:101]
	s_mov_b32 m0, s36
	ds_read_b128 v[166:169], v130 offset:2048
	ds_read_b128 v[170:173], v130 offset:3072
	global_load_lds_dwordx4 v142, s[100:101]
	v_add_u32_e32 v130, s31, v159
	ds_read_b128 v[174:177], v130
	ds_read_b128 v[182:185], v130 offset:1024
	ds_read_b128 v[186:189], v130 offset:2048
	ds_read_b128 v[190:193], v130 offset:3072
	ds_read_b128 v[194:197], v161 offset:32768
	ds_read_b128 v[198:201], v161 offset:33792
	ds_read_b128 v[202:205], v161 offset:34816
	ds_read_b128 v[206:209], v161 offset:35840
	ds_read_b128 v[210:213], v161 offset:36864
	ds_read_b128 v[214:217], v161 offset:37888
	ds_read_b128 v[218:221], v161 offset:38912
	ds_read_b128 v[222:225], v161 offset:39936
	s_waitcnt vmcnt(8)
	s_waitcnt lgkmcnt(0)
	s_barrier
	s_setprio 1
	s_waitcnt lgkmcnt(0)
	v_mfma_f32_16x16x32_bf16 v[126:129], v[152:155], v[194:197], v[126:129]
	v_mfma_f32_16x16x32_bf16 v[126:129], v[162:165], v[198:201], v[126:129]
	v_mfma_f32_16x16x32_bf16 v[122:125], v[166:169], v[194:197], v[122:125]
	v_mfma_f32_16x16x32_bf16 v[122:125], v[170:173], v[198:201], v[122:125]
	v_mfma_f32_16x16x32_bf16 v[110:113], v[152:155], v[202:205], v[110:113]
	v_mfma_f32_16x16x32_bf16 v[110:113], v[162:165], v[206:209], v[110:113]
	v_mfma_f32_16x16x32_bf16 v[106:109], v[166:169], v[202:205], v[106:109]
	v_mfma_f32_16x16x32_bf16 v[106:109], v[170:173], v[206:209], v[106:109]
	v_mfma_f32_16x16x32_bf16 v[94:97], v[152:155], v[210:213], v[94:97]
	v_mfma_f32_16x16x32_bf16 v[94:97], v[162:165], v[214:217], v[94:97]
	v_mfma_f32_16x16x32_bf16 v[90:93], v[166:169], v[210:213], v[90:93]
	v_mfma_f32_16x16x32_bf16 v[90:93], v[170:173], v[214:217], v[90:93]
	v_mfma_f32_16x16x32_bf16 v[78:81], v[152:155], v[218:221], v[78:81]
	v_mfma_f32_16x16x32_bf16 v[78:81], v[162:165], v[222:225], v[78:81]
	v_mfma_f32_16x16x32_bf16 v[74:77], v[166:169], v[218:221], v[74:77]
	v_mfma_f32_16x16x32_bf16 v[74:77], v[170:173], v[222:225], v[74:77]
	s_setprio 0
	s_setprio 1
	v_mfma_f32_16x16x32_bf16 v[118:121], v[174:177], v[194:197], v[118:121]
	v_mfma_f32_16x16x32_bf16 v[118:121], v[182:185], v[198:201], v[118:121]
	v_mfma_f32_16x16x32_bf16 v[114:117], v[186:189], v[194:197], v[114:117]
	v_mfma_f32_16x16x32_bf16 v[114:117], v[190:193], v[198:201], v[114:117]
	v_mfma_f32_16x16x32_bf16 v[102:105], v[174:177], v[202:205], v[102:105]
	v_mfma_f32_16x16x32_bf16 v[102:105], v[182:185], v[206:209], v[102:105]
	v_mfma_f32_16x16x32_bf16 v[98:101], v[186:189], v[202:205], v[98:101]
	v_mfma_f32_16x16x32_bf16 v[98:101], v[190:193], v[206:209], v[98:101]
	v_mfma_f32_16x16x32_bf16 v[86:89], v[174:177], v[210:213], v[86:89]
	v_mfma_f32_16x16x32_bf16 v[86:89], v[182:185], v[214:217], v[86:89]
	v_mfma_f32_16x16x32_bf16 v[82:85], v[186:189], v[210:213], v[82:85]
	v_mfma_f32_16x16x32_bf16 v[82:85], v[190:193], v[214:217], v[82:85]
	v_mfma_f32_16x16x32_bf16 v[70:73], v[174:177], v[218:221], v[70:73]
	v_mfma_f32_16x16x32_bf16 v[70:73], v[182:185], v[222:225], v[70:73]
	v_mfma_f32_16x16x32_bf16 v[66:69], v[186:189], v[218:221], v[66:69]
	v_mfma_f32_16x16x32_bf16 v[66:69], v[190:193], v[222:225], v[66:69]
	s_setprio 0
	s_barrier
	s_add_u32 s14, s14, 0x80
	s_addc_u32 s15, s15, 0
	s_add_i32 m0, s28, 0x18000
	ds_read_b128 v[194:197], v161 offset:49152
	ds_read_b128 v[198:201], v161 offset:50176
	global_load_lds_dwordx4 v144, s[14:15]
	s_add_i32 m0, s28, 0x1a000
	s_add_u32 s98, s98, 0x80
	s_addc_u32 s99, s99, 0
	ds_read_b128 v[202:205], v161 offset:51200
	global_load_lds_dwordx4 v140, s[14:15]
	s_add_i32 m0, s28, 0x1c000
	ds_read_b128 v[206:209], v161 offset:52224
	ds_read_b128 v[210:213], v161 offset:53248
	global_load_lds_dwordx4 v144, s[98:99]
	s_add_i32 m0, s28, 0x1e000
	s_add_u32 s16, s16, 0x80
	s_addc_u32 s17, s17, 0
	ds_read_b128 v[214:217], v161 offset:54272
	ds_read_b128 v[218:221], v161 offset:55296
	global_load_lds_dwordx4 v140, s[98:99]
	s_mov_b32 m0, s39
	ds_read_b128 v[222:225], v161 offset:56320
	global_load_lds_dwordx4 v146, s[16:17]
	s_mov_b32 m0, s44
	s_nop 0
	global_load_lds_dwordx4 v142, s[16:17]
	s_waitcnt vmcnt(8)
	s_waitcnt lgkmcnt(0)
	s_barrier
	s_setprio 1
	s_waitcnt lgkmcnt(0)
	v_mfma_f32_16x16x32_bf16 v[62:65], v[152:155], v[194:197], v[62:65]
	v_mfma_f32_16x16x32_bf16 v[62:65], v[162:165], v[198:201], v[62:65]
	v_mfma_f32_16x16x32_bf16 v[58:61], v[166:169], v[194:197], v[58:61]
	v_mfma_f32_16x16x32_bf16 v[58:61], v[170:173], v[198:201], v[58:61]
	v_mfma_f32_16x16x32_bf16 v[46:49], v[152:155], v[202:205], v[46:49]
	v_mfma_f32_16x16x32_bf16 v[46:49], v[162:165], v[206:209], v[46:49]
	v_mfma_f32_16x16x32_bf16 v[42:45], v[166:169], v[202:205], v[42:45]
	v_mfma_f32_16x16x32_bf16 v[42:45], v[170:173], v[206:209], v[42:45]
	v_mfma_f32_16x16x32_bf16 v[30:33], v[152:155], v[210:213], v[30:33]
	v_mfma_f32_16x16x32_bf16 v[30:33], v[162:165], v[214:217], v[30:33]
	v_mfma_f32_16x16x32_bf16 v[26:29], v[166:169], v[210:213], v[26:29]
	v_mfma_f32_16x16x32_bf16 v[26:29], v[170:173], v[214:217], v[26:29]
	v_mfma_f32_16x16x32_bf16 v[14:17], v[152:155], v[218:221], v[14:17]
	v_mfma_f32_16x16x32_bf16 v[14:17], v[162:165], v[222:225], v[14:17]
	v_mfma_f32_16x16x32_bf16 v[10:13], v[166:169], v[218:221], v[10:13]
	v_mfma_f32_16x16x32_bf16 v[10:13], v[170:173], v[222:225], v[10:13]
	s_setprio 0
	s_setprio 1
	v_mfma_f32_16x16x32_bf16 v[54:57], v[174:177], v[194:197], v[54:57]
	v_mfma_f32_16x16x32_bf16 v[54:57], v[182:185], v[198:201], v[54:57]
	v_mfma_f32_16x16x32_bf16 v[50:53], v[186:189], v[194:197], v[50:53]
	v_mfma_f32_16x16x32_bf16 v[50:53], v[190:193], v[198:201], v[50:53]
	v_mfma_f32_16x16x32_bf16 v[38:41], v[174:177], v[202:205], v[38:41]
	v_mfma_f32_16x16x32_bf16 v[38:41], v[182:185], v[206:209], v[38:41]
	v_mfma_f32_16x16x32_bf16 v[34:37], v[186:189], v[202:205], v[34:37]
	v_mfma_f32_16x16x32_bf16 v[34:37], v[190:193], v[206:209], v[34:37]
	v_mfma_f32_16x16x32_bf16 v[22:25], v[174:177], v[210:213], v[22:25]
	v_mfma_f32_16x16x32_bf16 v[22:25], v[182:185], v[214:217], v[22:25]
	v_mfma_f32_16x16x32_bf16 v[18:21], v[186:189], v[210:213], v[18:21]
	v_mfma_f32_16x16x32_bf16 v[18:21], v[190:193], v[214:217], v[18:21]
	v_mfma_f32_16x16x32_bf16 v[6:9], v[174:177], v[218:221], v[6:9]
	v_mfma_f32_16x16x32_bf16 v[6:9], v[182:185], v[222:225], v[6:9]
	v_mfma_f32_16x16x32_bf16 v[2:5], v[186:189], v[218:221], v[2:5]
	v_mfma_f32_16x16x32_bf16 v[2:5], v[190:193], v[222:225], v[2:5]
	s_setprio 0
	s_barrier
	s_add_i32 s35, s35, 2
	s_add_u32 s12, s12, 0x100
	s_addc_u32 s13, s13, 0
	s_add_u32 s0, s0, 0x100
	s_addc_u32 s1, s1, 0
	s_cmp_gt_u32 s35, 61
	s_cbranch_scc0 .LBB0_572
	s_and_b64 vcc, exec, s[10:11]
	s_cbranch_vccz .LBB0_575
	s_barrier

.LBB0_882:
	s_add_u32 s20, s10, 0xfff00080
	s_addc_u32 s21, s11, -1
	s_add_i32 s22, 0, 0x10000
	s_cmp_eq_u32 s12, 60
	s_cselect_b32 s43, s55, s21
	s_cselect_b32 s42, s54, s20
	v_add_u32_e32 v2, s22, v155
	s_cselect_b32 s39, s37, s1
	s_cselect_b32 s38, s36, s0
	s_add_i32 s23, 0, 0x14000
	s_add_i32 m0, s29, 0xc000
	ds_read_b128 v[146:149], v2
	ds_read_b128 v[150:153], v2 offset:1024
	global_load_lds_dwordx4 v140, s[10:11]
	s_add_i32 m0, s29, 0xe000
	ds_read_b128 v[158:161], v2 offset:2048
	ds_read_b128 v[162:165], v2 offset:3072
	global_load_lds_dwordx4 v142, s[10:11]
	v_add_u32_e32 v2, s23, v155
	ds_read_b128 v[166:169], v2
	ds_read_b128 v[170:173], v2 offset:1024
	ds_read_b128 v[174:177], v2 offset:2048
	ds_read_b128 v[186:189], v2 offset:3072
	ds_read_b128 v[190:193], v157
	ds_read_b128 v[194:197], v157 offset:1024
	ds_read_b128 v[198:201], v157 offset:2048
	ds_read_b128 v[202:205], v157 offset:3072
	ds_read_b128 v[206:209], v157 offset:4096
	ds_read_b128 v[210:213], v157 offset:5120
	ds_read_b128 v[214:217], v157 offset:6144
	ds_read_b128 v[218:221], v157 offset:7168
	s_waitcnt vmcnt(8)
	s_waitcnt lgkmcnt(0)
	s_barrier
	s_setprio 1
	s_waitcnt lgkmcnt(0)
	v_mfma_f32_16x16x32_bf16 v[128:131], v[146:149], v[190:193], v[128:131]
	v_mfma_f32_16x16x32_bf16 v[128:131], v[150:153], v[194:197], v[128:131]
	v_mfma_f32_16x16x32_bf16 v[124:127], v[158:161], v[190:193], v[124:127]
	v_mfma_f32_16x16x32_bf16 v[124:127], v[162:165], v[194:197], v[124:127]
	v_mfma_f32_16x16x32_bf16 v[112:115], v[146:149], v[198:201], v[112:115]
	v_mfma_f32_16x16x32_bf16 v[112:115], v[150:153], v[202:205], v[112:115]
	v_mfma_f32_16x16x32_bf16 v[108:111], v[158:161], v[198:201], v[108:111]
	v_mfma_f32_16x16x32_bf16 v[108:111], v[162:165], v[202:205], v[108:111]
	v_mfma_f32_16x16x32_bf16 v[96:99], v[146:149], v[206:209], v[96:99]
	v_mfma_f32_16x16x32_bf16 v[96:99], v[150:153], v[210:213], v[96:99]
	v_mfma_f32_16x16x32_bf16 v[92:95], v[158:161], v[206:209], v[92:95]
	v_mfma_f32_16x16x32_bf16 v[92:95], v[162:165], v[210:213], v[92:95]
	v_mfma_f32_16x16x32_bf16 v[80:83], v[146:149], v[214:217], v[80:83]
	v_mfma_f32_16x16x32_bf16 v[80:83], v[150:153], v[218:221], v[80:83]
	v_mfma_f32_16x16x32_bf16 v[76:79], v[158:161], v[214:217], v[76:79]
	v_mfma_f32_16x16x32_bf16 v[76:79], v[162:165], v[218:221], v[76:79]
	s_setprio 0
	s_setprio 1
	v_mfma_f32_16x16x32_bf16 v[120:123], v[166:169], v[190:193], v[120:123]
	v_mfma_f32_16x16x32_bf16 v[120:123], v[170:173], v[194:197], v[120:123]
	v_mfma_f32_16x16x32_bf16 v[116:119], v[174:177], v[190:193], v[116:119]
	v_mfma_f32_16x16x32_bf16 v[116:119], v[186:189], v[194:197], v[116:119]
	v_mfma_f32_16x16x32_bf16 v[104:107], v[166:169], v[198:201], v[104:107]
	v_mfma_f32_16x16x32_bf16 v[104:107], v[170:173], v[202:205], v[104:107]
	v_mfma_f32_16x16x32_bf16 v[100:103], v[174:177], v[198:201], v[100:103]
	v_mfma_f32_16x16x32_bf16 v[100:103], v[186:189], v[202:205], v[100:103]
	v_mfma_f32_16x16x32_bf16 v[88:91], v[166:169], v[206:209], v[88:91]
	v_mfma_f32_16x16x32_bf16 v[88:91], v[170:173], v[210:213], v[88:91]
	v_mfma_f32_16x16x32_bf16 v[84:87], v[174:177], v[206:209], v[84:87]
	v_mfma_f32_16x16x32_bf16 v[84:87], v[186:189], v[210:213], v[84:87]
	v_mfma_f32_16x16x32_bf16 v[72:75], v[166:169], v[214:217], v[72:75]
	v_mfma_f32_16x16x32_bf16 v[72:75], v[170:173], v[218:221], v[72:75]
	v_mfma_f32_16x16x32_bf16 v[68:71], v[174:177], v[214:217], v[68:71]
	v_mfma_f32_16x16x32_bf16 v[68:71], v[186:189], v[218:221], v[68:71]
	s_setprio 0
	s_barrier
	s_add_i32 m0, s58, 0x10000
	ds_read_b128 v[190:193], v157 offset:16384
	ds_read_b128 v[194:197], v157 offset:17408
	global_load_lds_dwordx4 v134, s[38:39]
	s_add_i32 m0, s58, 0x12000
	s_add_u32 s98, s38, 0x100000
	s_addc_u32 s99, s39, 0
	ds_read_b128 v[198:201], v157 offset:18432
	global_load_lds_dwordx4 v138, s[38:39]
	s_add_i32 m0, s58, 0x14000
	ds_read_b128 v[202:205], v157 offset:19456
	ds_read_b128 v[206:209], v157 offset:20480
	global_load_lds_dwordx4 v134, s[98:99]
	s_add_i32 m0, s58, 0x16000
	ds_read_b128 v[210:213], v157 offset:21504
	ds_read_b128 v[214:217], v157 offset:22528
	global_load_lds_dwordx4 v138, s[98:99]
	s_mov_b32 m0, s29
	ds_read_b128 v[218:221], v157 offset:23552
	global_load_lds_dwordx4 v132, s[42:43]
	s_mov_b32 m0, s31
	s_nop 0
	global_load_lds_dwordx4 v136, s[42:43]
	s_waitcnt vmcnt(8)
	s_waitcnt lgkmcnt(0)
	s_barrier
	s_setprio 1
	s_waitcnt lgkmcnt(0)
	v_mfma_f32_16x16x32_bf16 v[64:67], v[146:149], v[190:193], v[64:67]
	v_mfma_f32_16x16x32_bf16 v[64:67], v[150:153], v[194:197], v[64:67]
	v_mfma_f32_16x16x32_bf16 v[60:63], v[158:161], v[190:193], v[60:63]
	v_mfma_f32_16x16x32_bf16 v[60:63], v[162:165], v[194:197], v[60:63]
	v_mfma_f32_16x16x32_bf16 v[48:51], v[146:149], v[198:201], v[48:51]
	v_mfma_f32_16x16x32_bf16 v[48:51], v[150:153], v[202:205], v[48:51]
	v_mfma_f32_16x16x32_bf16 v[44:47], v[158:161], v[198:201], v[44:47]
	v_mfma_f32_16x16x32_bf16 v[44:47], v[162:165], v[202:205], v[44:47]
	v_mfma_f32_16x16x32_bf16 v[32:35], v[146:149], v[206:209], v[32:35]
	v_mfma_f32_16x16x32_bf16 v[32:35], v[150:153], v[210:213], v[32:35]
	v_mfma_f32_16x16x32_bf16 v[28:31], v[158:161], v[206:209], v[28:31]
	v_mfma_f32_16x16x32_bf16 v[28:31], v[162:165], v[210:213], v[28:31]
	v_mfma_f32_16x16x32_bf16 v[16:19], v[146:149], v[214:217], v[16:19]
	v_mfma_f32_16x16x32_bf16 v[16:19], v[150:153], v[218:221], v[16:19]
	v_mfma_f32_16x16x32_bf16 v[12:15], v[158:161], v[214:217], v[12:15]
	v_mfma_f32_16x16x32_bf16 v[12:15], v[162:165], v[218:221], v[12:15]
	s_setprio 0
	s_setprio 1
	v_mfma_f32_16x16x32_bf16 v[56:59], v[166:169], v[190:193], v[56:59]
	v_mfma_f32_16x16x32_bf16 v[56:59], v[170:173], v[194:197], v[56:59]
	v_mfma_f32_16x16x32_bf16 v[52:55], v[174:177], v[190:193], v[52:55]
	v_mfma_f32_16x16x32_bf16 v[52:55], v[186:189], v[194:197], v[52:55]
	v_mfma_f32_16x16x32_bf16 v[40:43], v[166:169], v[198:201], v[40:43]
	v_mfma_f32_16x16x32_bf16 v[40:43], v[170:173], v[202:205], v[40:43]
	v_mfma_f32_16x16x32_bf16 v[36:39], v[174:177], v[198:201], v[36:39]
	v_mfma_f32_16x16x32_bf16 v[36:39], v[186:189], v[202:205], v[36:39]
	v_mfma_f32_16x16x32_bf16 v[24:27], v[166:169], v[206:209], v[24:27]
	v_mfma_f32_16x16x32_bf16 v[24:27], v[170:173], v[210:213], v[24:27]
	v_mfma_f32_16x16x32_bf16 v[20:23], v[174:177], v[206:209], v[20:23]
	v_mfma_f32_16x16x32_bf16 v[20:23], v[186:189], v[210:213], v[20:23]
	v_mfma_f32_16x16x32_bf16 v[8:11], v[166:169], v[214:217], v[8:11]
	v_mfma_f32_16x16x32_bf16 v[8:11], v[170:173], v[218:221], v[8:11]
	v_mfma_f32_16x16x32_bf16 v[4:7], v[174:177], v[214:217], v[4:7]
	v_mfma_f32_16x16x32_bf16 v[4:7], v[186:189], v[218:221], v[4:7]
	s_setprio 0
	s_barrier
	s_add_u32 s100, s42, 0x100000
	s_addc_u32 s101, s43, 0
	s_mov_b32 m0, s59
	s_add_i32 s22, 0, 0x18000
	v_add_u32_e32 v2, s22, v155
	s_add_i32 s23, 0, 0x1c000
	ds_read_b128 v[146:149], v2
	ds_read_b128 v[150:153], v2 offset:1024
	global_load_lds_dwordx4 v132, s[100:101]
	s_mov_b32 m0, s94
	ds_read_b128 v[158:161], v2 offset:2048
	ds_read_b128 v[162:165], v2 offset:3072
	global_load_lds_dwordx4 v136, s[100:101]
	v_add_u32_e32 v2, s23, v155
	ds_read_b128 v[166:169], v2
	ds_read_b128 v[170:173], v2 offset:1024
	ds_read_b128 v[174:177], v2 offset:2048
	ds_read_b128 v[186:189], v2 offset:3072
	ds_read_b128 v[190:193], v157 offset:32768
	ds_read_b128 v[194:197], v157 offset:33792
	ds_read_b128 v[198:201], v157 offset:34816
	ds_read_b128 v[202:205], v157 offset:35840
	ds_read_b128 v[206:209], v157 offset:36864
	ds_read_b128 v[210:213], v157 offset:37888
	ds_read_b128 v[214:217], v157 offset:38912
	ds_read_b128 v[218:221], v157 offset:39936
	s_waitcnt vmcnt(8)
	s_waitcnt lgkmcnt(0)
	s_barrier
	s_setprio 1
	s_waitcnt lgkmcnt(0)
	v_mfma_f32_16x16x32_bf16 v[128:131], v[146:149], v[190:193], v[128:131]
	v_mfma_f32_16x16x32_bf16 v[128:131], v[150:153], v[194:197], v[128:131]
	v_mfma_f32_16x16x32_bf16 v[124:127], v[158:161], v[190:193], v[124:127]
	v_mfma_f32_16x16x32_bf16 v[124:127], v[162:165], v[194:197], v[124:127]
	v_mfma_f32_16x16x32_bf16 v[112:115], v[146:149], v[198:201], v[112:115]
	v_mfma_f32_16x16x32_bf16 v[112:115], v[150:153], v[202:205], v[112:115]
	v_mfma_f32_16x16x32_bf16 v[108:111], v[158:161], v[198:201], v[108:111]
	v_mfma_f32_16x16x32_bf16 v[108:111], v[162:165], v[202:205], v[108:111]
	v_mfma_f32_16x16x32_bf16 v[96:99], v[146:149], v[206:209], v[96:99]
	v_mfma_f32_16x16x32_bf16 v[96:99], v[150:153], v[210:213], v[96:99]
	v_mfma_f32_16x16x32_bf16 v[92:95], v[158:161], v[206:209], v[92:95]
	v_mfma_f32_16x16x32_bf16 v[92:95], v[162:165], v[210:213], v[92:95]
	v_mfma_f32_16x16x32_bf16 v[80:83], v[146:149], v[214:217], v[80:83]
	v_mfma_f32_16x16x32_bf16 v[80:83], v[150:153], v[218:221], v[80:83]
	v_mfma_f32_16x16x32_bf16 v[76:79], v[158:161], v[214:217], v[76:79]
	v_mfma_f32_16x16x32_bf16 v[76:79], v[162:165], v[218:221], v[76:79]
	s_setprio 0
	s_setprio 1
	v_mfma_f32_16x16x32_bf16 v[120:123], v[166:169], v[190:193], v[120:123]
	v_mfma_f32_16x16x32_bf16 v[120:123], v[170:173], v[194:197], v[120:123]
	v_mfma_f32_16x16x32_bf16 v[116:119], v[174:177], v[190:193], v[116:119]
	v_mfma_f32_16x16x32_bf16 v[116:119], v[186:189], v[194:197], v[116:119]
	v_mfma_f32_16x16x32_bf16 v[104:107], v[166:169], v[198:201], v[104:107]
	v_mfma_f32_16x16x32_bf16 v[104:107], v[170:173], v[202:205], v[104:107]
	v_mfma_f32_16x16x32_bf16 v[100:103], v[174:177], v[198:201], v[100:103]
	v_mfma_f32_16x16x32_bf16 v[100:103], v[186:189], v[202:205], v[100:103]
	v_mfma_f32_16x16x32_bf16 v[88:91], v[166:169], v[206:209], v[88:91]
	v_mfma_f32_16x16x32_bf16 v[88:91], v[170:173], v[210:213], v[88:91]
	v_mfma_f32_16x16x32_bf16 v[84:87], v[174:177], v[206:209], v[84:87]
	v_mfma_f32_16x16x32_bf16 v[84:87], v[186:189], v[210:213], v[84:87]
	v_mfma_f32_16x16x32_bf16 v[72:75], v[166:169], v[214:217], v[72:75]
	v_mfma_f32_16x16x32_bf16 v[72:75], v[170:173], v[218:221], v[72:75]
	v_mfma_f32_16x16x32_bf16 v[68:71], v[174:177], v[214:217], v[68:71]
	v_mfma_f32_16x16x32_bf16 v[68:71], v[186:189], v[218:221], v[68:71]
	s_setprio 0
	s_barrier
	s_add_u32 s38, s38, 0x80
	s_addc_u32 s39, s39, 0
	s_add_i32 m0, s58, 0x18000
	ds_read_b128 v[190:193], v157 offset:49152
	ds_read_b128 v[194:197], v157 offset:50176
	global_load_lds_dwordx4 v134, s[38:39]
	s_add_i32 m0, s58, 0x1a000
	s_add_u32 s98, s98, 0x80
	s_addc_u32 s99, s99, 0
	ds_read_b128 v[198:201], v157 offset:51200
	global_load_lds_dwordx4 v138, s[38:39]
	s_add_i32 m0, s58, 0x1c000
	ds_read_b128 v[202:205], v157 offset:52224
	ds_read_b128 v[206:209], v157 offset:53248
	global_load_lds_dwordx4 v134, s[98:99]
	s_add_i32 m0, s58, 0x1e000
	s_add_u32 s42, s42, 0x80
	s_addc_u32 s43, s43, 0
	ds_read_b128 v[210:213], v157 offset:54272
	ds_read_b128 v[214:217], v157 offset:55296
	global_load_lds_dwordx4 v138, s[98:99]
	s_mov_b32 m0, s14
	ds_read_b128 v[218:221], v157 offset:56320
	global_load_lds_dwordx4 v132, s[42:43]
	s_mov_b32 m0, s15
	s_nop 0
	global_load_lds_dwordx4 v136, s[42:43]
	s_waitcnt vmcnt(8)
	s_waitcnt lgkmcnt(0)
	s_barrier
	s_setprio 1
	s_waitcnt lgkmcnt(0)
	v_mfma_f32_16x16x32_bf16 v[64:67], v[146:149], v[190:193], v[64:67]
	v_mfma_f32_16x16x32_bf16 v[64:67], v[150:153], v[194:197], v[64:67]
	v_mfma_f32_16x16x32_bf16 v[60:63], v[158:161], v[190:193], v[60:63]
	v_mfma_f32_16x16x32_bf16 v[60:63], v[162:165], v[194:197], v[60:63]
	v_mfma_f32_16x16x32_bf16 v[48:51], v[146:149], v[198:201], v[48:51]
	v_mfma_f32_16x16x32_bf16 v[48:51], v[150:153], v[202:205], v[48:51]
	v_mfma_f32_16x16x32_bf16 v[44:47], v[158:161], v[198:201], v[44:47]
	v_mfma_f32_16x16x32_bf16 v[44:47], v[162:165], v[202:205], v[44:47]
	v_mfma_f32_16x16x32_bf16 v[32:35], v[146:149], v[206:209], v[32:35]
	v_mfma_f32_16x16x32_bf16 v[32:35], v[150:153], v[210:213], v[32:35]
	v_mfma_f32_16x16x32_bf16 v[28:31], v[158:161], v[206:209], v[28:31]
	v_mfma_f32_16x16x32_bf16 v[28:31], v[162:165], v[210:213], v[28:31]
	v_mfma_f32_16x16x32_bf16 v[16:19], v[146:149], v[214:217], v[16:19]
	v_mfma_f32_16x16x32_bf16 v[16:19], v[150:153], v[218:221], v[16:19]
	v_mfma_f32_16x16x32_bf16 v[12:15], v[158:161], v[214:217], v[12:15]
	v_mfma_f32_16x16x32_bf16 v[12:15], v[162:165], v[218:221], v[12:15]
	s_setprio 0
	s_setprio 1
	v_mfma_f32_16x16x32_bf16 v[56:59], v[166:169], v[190:193], v[56:59]
	v_mfma_f32_16x16x32_bf16 v[56:59], v[170:173], v[194:197], v[56:59]
	v_mfma_f32_16x16x32_bf16 v[52:55], v[174:177], v[190:193], v[52:55]
	v_mfma_f32_16x16x32_bf16 v[52:55], v[186:189], v[194:197], v[52:55]
	v_mfma_f32_16x16x32_bf16 v[40:43], v[166:169], v[198:201], v[40:43]
	v_mfma_f32_16x16x32_bf16 v[40:43], v[170:173], v[202:205], v[40:43]
	v_mfma_f32_16x16x32_bf16 v[36:39], v[174:177], v[198:201], v[36:39]
	v_mfma_f32_16x16x32_bf16 v[36:39], v[186:189], v[202:205], v[36:39]
	v_mfma_f32_16x16x32_bf16 v[24:27], v[166:169], v[206:209], v[24:27]
	v_mfma_f32_16x16x32_bf16 v[24:27], v[170:173], v[210:213], v[24:27]
	v_mfma_f32_16x16x32_bf16 v[20:23], v[174:177], v[206:209], v[20:23]
	v_mfma_f32_16x16x32_bf16 v[20:23], v[186:189], v[210:213], v[20:23]
	v_mfma_f32_16x16x32_bf16 v[8:11], v[166:169], v[214:217], v[8:11]
	v_mfma_f32_16x16x32_bf16 v[8:11], v[170:173], v[218:221], v[8:11]
	v_mfma_f32_16x16x32_bf16 v[4:7], v[174:177], v[214:217], v[4:7]
	v_mfma_f32_16x16x32_bf16 v[4:7], v[186:189], v[218:221], v[4:7]
	s_setprio 0
	s_barrier
	s_add_i32 s12, s12, 2
	s_add_u32 s10, s10, 0x100
	s_addc_u32 s11, s11, 0
	s_add_u32 s0, s0, 0x100
	s_addc_u32 s1, s1, 0
	s_cmp_gt_u32 s12, 61
	s_cbranch_scc0 .LBB0_882
	s_and_b64 vcc, exec, s[48:49]
	s_cbranch_vccz .LBB0_885
	s_barrier

.LBB0_1226:
	s_add_u32 s21, s10, 0xfff00080
	s_addc_u32 s22, s11, -1
	s_add_i32 s23, 0, 0x10000
	s_cmp_eq_u32 s20, 60
	s_cselect_b32 s31, s53, s22
	s_cselect_b32 s30, s52, s21
	v_add_u32_e32 v2, s23, v151
	s_cselect_b32 s29, s55, s1
	s_cselect_b32 s28, s54, s0
	s_add_i32 s21, 0, 0x14000
	s_add_i32 m0, s8, 0xc000
	ds_read_b128 v[144:147], v2
	ds_read_b128 v[154:157], v2 offset:1024
	global_load_lds_dwordx4 v140, s[10:11]
	s_add_i32 m0, s8, 0xe000
	ds_read_b128 v[158:161], v2 offset:2048
	ds_read_b128 v[162:165], v2 offset:3072
	global_load_lds_dwordx4 v142, s[10:11]
	v_add_u32_e32 v2, s21, v151
	ds_read_b128 v[166:169], v2
	ds_read_b128 v[170:173], v2 offset:1024
	ds_read_b128 v[174:177], v2 offset:2048
	ds_read_b128 v[186:189], v2 offset:3072
	ds_read_b128 v[190:193], v153
	ds_read_b128 v[194:197], v153 offset:1024
	ds_read_b128 v[198:201], v153 offset:2048
	ds_read_b128 v[202:205], v153 offset:3072
	ds_read_b128 v[206:209], v153 offset:4096
	ds_read_b128 v[210:213], v153 offset:5120
	ds_read_b128 v[214:217], v153 offset:6144
	ds_read_b128 v[218:221], v153 offset:7168
	s_waitcnt vmcnt(8)
	s_waitcnt lgkmcnt(0)
	s_barrier
	s_setprio 1
	s_waitcnt lgkmcnt(0)
	v_mfma_f32_16x16x32_bf16 v[128:131], v[144:147], v[190:193], v[128:131]
	v_mfma_f32_16x16x32_bf16 v[128:131], v[154:157], v[194:197], v[128:131]
	v_mfma_f32_16x16x32_bf16 v[124:127], v[158:161], v[190:193], v[124:127]
	v_mfma_f32_16x16x32_bf16 v[124:127], v[162:165], v[194:197], v[124:127]
	v_mfma_f32_16x16x32_bf16 v[112:115], v[144:147], v[198:201], v[112:115]
	v_mfma_f32_16x16x32_bf16 v[112:115], v[154:157], v[202:205], v[112:115]
	v_mfma_f32_16x16x32_bf16 v[108:111], v[158:161], v[198:201], v[108:111]
	v_mfma_f32_16x16x32_bf16 v[108:111], v[162:165], v[202:205], v[108:111]
	v_mfma_f32_16x16x32_bf16 v[96:99], v[144:147], v[206:209], v[96:99]
	v_mfma_f32_16x16x32_bf16 v[96:99], v[154:157], v[210:213], v[96:99]
	v_mfma_f32_16x16x32_bf16 v[92:95], v[158:161], v[206:209], v[92:95]
	v_mfma_f32_16x16x32_bf16 v[92:95], v[162:165], v[210:213], v[92:95]
	v_mfma_f32_16x16x32_bf16 v[80:83], v[144:147], v[214:217], v[80:83]
	v_mfma_f32_16x16x32_bf16 v[80:83], v[154:157], v[218:221], v[80:83]
	v_mfma_f32_16x16x32_bf16 v[76:79], v[158:161], v[214:217], v[76:79]
	v_mfma_f32_16x16x32_bf16 v[76:79], v[162:165], v[218:221], v[76:79]
	s_setprio 0
	s_setprio 1
	v_mfma_f32_16x16x32_bf16 v[120:123], v[166:169], v[190:193], v[120:123]
	v_mfma_f32_16x16x32_bf16 v[120:123], v[170:173], v[194:197], v[120:123]
	v_mfma_f32_16x16x32_bf16 v[116:119], v[174:177], v[190:193], v[116:119]
	v_mfma_f32_16x16x32_bf16 v[116:119], v[186:189], v[194:197], v[116:119]
	v_mfma_f32_16x16x32_bf16 v[104:107], v[166:169], v[198:201], v[104:107]
	v_mfma_f32_16x16x32_bf16 v[104:107], v[170:173], v[202:205], v[104:107]
	v_mfma_f32_16x16x32_bf16 v[100:103], v[174:177], v[198:201], v[100:103]
	v_mfma_f32_16x16x32_bf16 v[100:103], v[186:189], v[202:205], v[100:103]
	v_mfma_f32_16x16x32_bf16 v[88:91], v[166:169], v[206:209], v[88:91]
	v_mfma_f32_16x16x32_bf16 v[88:91], v[170:173], v[210:213], v[88:91]
	v_mfma_f32_16x16x32_bf16 v[84:87], v[174:177], v[206:209], v[84:87]
	v_mfma_f32_16x16x32_bf16 v[84:87], v[186:189], v[210:213], v[84:87]
	v_mfma_f32_16x16x32_bf16 v[72:75], v[166:169], v[214:217], v[72:75]
	v_mfma_f32_16x16x32_bf16 v[72:75], v[170:173], v[218:221], v[72:75]
	v_mfma_f32_16x16x32_bf16 v[68:71], v[174:177], v[214:217], v[68:71]
	v_mfma_f32_16x16x32_bf16 v[68:71], v[186:189], v[218:221], v[68:71]
	s_setprio 0
	s_barrier
	s_add_i32 m0, s38, 0x10000
	ds_read_b128 v[190:193], v153 offset:16384
	ds_read_b128 v[194:197], v153 offset:17408
	global_load_lds_dwordx4 v136, s[28:29]
	s_add_i32 m0, s38, 0x12000
	s_add_u32 s98, s28, 0x100000
	s_addc_u32 s99, s29, 0
	ds_read_b128 v[198:201], v153 offset:18432
	global_load_lds_dwordx4 v132, s[28:29]
	s_add_i32 m0, s38, 0x14000
	ds_read_b128 v[202:205], v153 offset:19456
	ds_read_b128 v[206:209], v153 offset:20480
	global_load_lds_dwordx4 v136, s[98:99]
	s_add_i32 m0, s38, 0x16000
	ds_read_b128 v[210:213], v153 offset:21504
	ds_read_b128 v[214:217], v153 offset:22528
	global_load_lds_dwordx4 v132, s[98:99]
	s_mov_b32 m0, s8
	ds_read_b128 v[218:221], v153 offset:23552
	global_load_lds_dwordx4 v138, s[30:31]
	s_mov_b32 m0, s9
	s_nop 0
	global_load_lds_dwordx4 v134, s[30:31]
	s_waitcnt vmcnt(8)
	s_waitcnt lgkmcnt(0)
	s_barrier
	s_setprio 1
	s_waitcnt lgkmcnt(0)
	v_mfma_f32_16x16x32_bf16 v[64:67], v[144:147], v[190:193], v[64:67]
	v_mfma_f32_16x16x32_bf16 v[64:67], v[154:157], v[194:197], v[64:67]
	v_mfma_f32_16x16x32_bf16 v[60:63], v[158:161], v[190:193], v[60:63]
	v_mfma_f32_16x16x32_bf16 v[60:63], v[162:165], v[194:197], v[60:63]
	v_mfma_f32_16x16x32_bf16 v[48:51], v[144:147], v[198:201], v[48:51]
	v_mfma_f32_16x16x32_bf16 v[48:51], v[154:157], v[202:205], v[48:51]
	v_mfma_f32_16x16x32_bf16 v[44:47], v[158:161], v[198:201], v[44:47]
	v_mfma_f32_16x16x32_bf16 v[44:47], v[162:165], v[202:205], v[44:47]
	v_mfma_f32_16x16x32_bf16 v[32:35], v[144:147], v[206:209], v[32:35]
	v_mfma_f32_16x16x32_bf16 v[32:35], v[154:157], v[210:213], v[32:35]
	v_mfma_f32_16x16x32_bf16 v[28:31], v[158:161], v[206:209], v[28:31]
	v_mfma_f32_16x16x32_bf16 v[28:31], v[162:165], v[210:213], v[28:31]
	v_mfma_f32_16x16x32_bf16 v[16:19], v[144:147], v[214:217], v[16:19]
	v_mfma_f32_16x16x32_bf16 v[16:19], v[154:157], v[218:221], v[16:19]
	v_mfma_f32_16x16x32_bf16 v[12:15], v[158:161], v[214:217], v[12:15]
	v_mfma_f32_16x16x32_bf16 v[12:15], v[162:165], v[218:221], v[12:15]
	s_setprio 0
	s_setprio 1
	v_mfma_f32_16x16x32_bf16 v[56:59], v[166:169], v[190:193], v[56:59]
	v_mfma_f32_16x16x32_bf16 v[56:59], v[170:173], v[194:197], v[56:59]
	v_mfma_f32_16x16x32_bf16 v[52:55], v[174:177], v[190:193], v[52:55]
	v_mfma_f32_16x16x32_bf16 v[52:55], v[186:189], v[194:197], v[52:55]
	v_mfma_f32_16x16x32_bf16 v[40:43], v[166:169], v[198:201], v[40:43]
	v_mfma_f32_16x16x32_bf16 v[40:43], v[170:173], v[202:205], v[40:43]
	v_mfma_f32_16x16x32_bf16 v[36:39], v[174:177], v[198:201], v[36:39]
	v_mfma_f32_16x16x32_bf16 v[36:39], v[186:189], v[202:205], v[36:39]
	v_mfma_f32_16x16x32_bf16 v[24:27], v[166:169], v[206:209], v[24:27]
	v_mfma_f32_16x16x32_bf16 v[24:27], v[170:173], v[210:213], v[24:27]
	v_mfma_f32_16x16x32_bf16 v[20:23], v[174:177], v[206:209], v[20:23]
	v_mfma_f32_16x16x32_bf16 v[20:23], v[186:189], v[210:213], v[20:23]
	v_mfma_f32_16x16x32_bf16 v[8:11], v[166:169], v[214:217], v[8:11]
	v_mfma_f32_16x16x32_bf16 v[8:11], v[170:173], v[218:221], v[8:11]
	v_mfma_f32_16x16x32_bf16 v[4:7], v[174:177], v[214:217], v[4:7]
	v_mfma_f32_16x16x32_bf16 v[4:7], v[186:189], v[218:221], v[4:7]
	s_setprio 0
	s_barrier
	s_add_u32 s100, s30, 0x100000
	s_addc_u32 s101, s31, 0
	s_mov_b32 m0, s16
	s_add_i32 s21, 0, 0x18000
	v_add_u32_e32 v2, s21, v151
	s_add_i32 s24, 0, 0x1c000
	ds_read_b128 v[144:147], v2
	ds_read_b128 v[154:157], v2 offset:1024
	global_load_lds_dwordx4 v138, s[100:101]
	s_mov_b32 m0, s17
	ds_read_b128 v[158:161], v2 offset:2048
	ds_read_b128 v[162:165], v2 offset:3072
	global_load_lds_dwordx4 v134, s[100:101]
	v_add_u32_e32 v2, s24, v151
	ds_read_b128 v[166:169], v2
	ds_read_b128 v[170:173], v2 offset:1024
	ds_read_b128 v[174:177], v2 offset:2048
	ds_read_b128 v[186:189], v2 offset:3072
	ds_read_b128 v[190:193], v153 offset:32768
	ds_read_b128 v[194:197], v153 offset:33792
	ds_read_b128 v[198:201], v153 offset:34816
	ds_read_b128 v[202:205], v153 offset:35840
	ds_read_b128 v[206:209], v153 offset:36864
	ds_read_b128 v[210:213], v153 offset:37888
	ds_read_b128 v[214:217], v153 offset:38912
	ds_read_b128 v[218:221], v153 offset:39936
	s_waitcnt vmcnt(8)
	s_waitcnt lgkmcnt(0)
	s_barrier
	s_setprio 1
	s_waitcnt lgkmcnt(0)
	v_mfma_f32_16x16x32_bf16 v[128:131], v[144:147], v[190:193], v[128:131]
	v_mfma_f32_16x16x32_bf16 v[128:131], v[154:157], v[194:197], v[128:131]
	v_mfma_f32_16x16x32_bf16 v[124:127], v[158:161], v[190:193], v[124:127]
	v_mfma_f32_16x16x32_bf16 v[124:127], v[162:165], v[194:197], v[124:127]
	v_mfma_f32_16x16x32_bf16 v[112:115], v[144:147], v[198:201], v[112:115]
	v_mfma_f32_16x16x32_bf16 v[112:115], v[154:157], v[202:205], v[112:115]
	v_mfma_f32_16x16x32_bf16 v[108:111], v[158:161], v[198:201], v[108:111]
	v_mfma_f32_16x16x32_bf16 v[108:111], v[162:165], v[202:205], v[108:111]
	v_mfma_f32_16x16x32_bf16 v[96:99], v[144:147], v[206:209], v[96:99]
	v_mfma_f32_16x16x32_bf16 v[96:99], v[154:157], v[210:213], v[96:99]
	v_mfma_f32_16x16x32_bf16 v[92:95], v[158:161], v[206:209], v[92:95]
	v_mfma_f32_16x16x32_bf16 v[92:95], v[162:165], v[210:213], v[92:95]
	v_mfma_f32_16x16x32_bf16 v[80:83], v[144:147], v[214:217], v[80:83]
	v_mfma_f32_16x16x32_bf16 v[80:83], v[154:157], v[218:221], v[80:83]
	v_mfma_f32_16x16x32_bf16 v[76:79], v[158:161], v[214:217], v[76:79]
	v_mfma_f32_16x16x32_bf16 v[76:79], v[162:165], v[218:221], v[76:79]
	s_setprio 0
	s_setprio 1
	v_mfma_f32_16x16x32_bf16 v[120:123], v[166:169], v[190:193], v[120:123]
	v_mfma_f32_16x16x32_bf16 v[120:123], v[170:173], v[194:197], v[120:123]
	v_mfma_f32_16x16x32_bf16 v[116:119], v[174:177], v[190:193], v[116:119]
	v_mfma_f32_16x16x32_bf16 v[116:119], v[186:189], v[194:197], v[116:119]
	v_mfma_f32_16x16x32_bf16 v[104:107], v[166:169], v[198:201], v[104:107]
	v_mfma_f32_16x16x32_bf16 v[104:107], v[170:173], v[202:205], v[104:107]
	v_mfma_f32_16x16x32_bf16 v[100:103], v[174:177], v[198:201], v[100:103]
	v_mfma_f32_16x16x32_bf16 v[100:103], v[186:189], v[202:205], v[100:103]
	v_mfma_f32_16x16x32_bf16 v[88:91], v[166:169], v[206:209], v[88:91]
	v_mfma_f32_16x16x32_bf16 v[88:91], v[170:173], v[210:213], v[88:91]
	v_mfma_f32_16x16x32_bf16 v[84:87], v[174:177], v[206:209], v[84:87]
	v_mfma_f32_16x16x32_bf16 v[84:87], v[186:189], v[210:213], v[84:87]
	v_mfma_f32_16x16x32_bf16 v[72:75], v[166:169], v[214:217], v[72:75]
	v_mfma_f32_16x16x32_bf16 v[72:75], v[170:173], v[218:221], v[72:75]
	v_mfma_f32_16x16x32_bf16 v[68:71], v[174:177], v[214:217], v[68:71]
	v_mfma_f32_16x16x32_bf16 v[68:71], v[186:189], v[218:221], v[68:71]
	s_setprio 0
	s_barrier
	s_add_u32 s28, s28, 0x80
	s_addc_u32 s29, s29, 0
	s_add_i32 m0, s38, 0x18000
	ds_read_b128 v[190:193], v153 offset:49152
	ds_read_b128 v[194:197], v153 offset:50176
	global_load_lds_dwordx4 v136, s[28:29]
	s_add_i32 m0, s38, 0x1a000
	s_add_u32 s98, s98, 0x80
	s_addc_u32 s99, s99, 0
	ds_read_b128 v[198:201], v153 offset:51200
	global_load_lds_dwordx4 v132, s[28:29]
	s_add_i32 m0, s38, 0x1c000
	ds_read_b128 v[202:205], v153 offset:52224
	ds_read_b128 v[206:209], v153 offset:53248
	global_load_lds_dwordx4 v136, s[98:99]
	s_add_i32 m0, s38, 0x1e000
	s_add_u32 s30, s30, 0x80
	s_addc_u32 s31, s31, 0
	ds_read_b128 v[210:213], v153 offset:54272
	ds_read_b128 v[214:217], v153 offset:55296
	global_load_lds_dwordx4 v132, s[98:99]
	s_mov_b32 m0, s45
	ds_read_b128 v[218:221], v153 offset:56320
	global_load_lds_dwordx4 v138, s[30:31]
	s_mov_b32 m0, s46
	s_nop 0
	global_load_lds_dwordx4 v134, s[30:31]
	s_waitcnt vmcnt(8)
	s_waitcnt lgkmcnt(0)
	s_barrier
	s_setprio 1
	s_waitcnt lgkmcnt(0)
	v_mfma_f32_16x16x32_bf16 v[64:67], v[144:147], v[190:193], v[64:67]
	v_mfma_f32_16x16x32_bf16 v[64:67], v[154:157], v[194:197], v[64:67]
	v_mfma_f32_16x16x32_bf16 v[60:63], v[158:161], v[190:193], v[60:63]
	v_mfma_f32_16x16x32_bf16 v[60:63], v[162:165], v[194:197], v[60:63]
	v_mfma_f32_16x16x32_bf16 v[48:51], v[144:147], v[198:201], v[48:51]
	v_mfma_f32_16x16x32_bf16 v[48:51], v[154:157], v[202:205], v[48:51]
	v_mfma_f32_16x16x32_bf16 v[44:47], v[158:161], v[198:201], v[44:47]
	v_mfma_f32_16x16x32_bf16 v[44:47], v[162:165], v[202:205], v[44:47]
	v_mfma_f32_16x16x32_bf16 v[32:35], v[144:147], v[206:209], v[32:35]
	v_mfma_f32_16x16x32_bf16 v[32:35], v[154:157], v[210:213], v[32:35]
	v_mfma_f32_16x16x32_bf16 v[28:31], v[158:161], v[206:209], v[28:31]
	v_mfma_f32_16x16x32_bf16 v[28:31], v[162:165], v[210:213], v[28:31]
	v_mfma_f32_16x16x32_bf16 v[16:19], v[144:147], v[214:217], v[16:19]
	v_mfma_f32_16x16x32_bf16 v[16:19], v[154:157], v[218:221], v[16:19]
	v_mfma_f32_16x16x32_bf16 v[12:15], v[158:161], v[214:217], v[12:15]
	v_mfma_f32_16x16x32_bf16 v[12:15], v[162:165], v[218:221], v[12:15]
	s_setprio 0
	s_setprio 1
	v_mfma_f32_16x16x32_bf16 v[56:59], v[166:169], v[190:193], v[56:59]
	v_mfma_f32_16x16x32_bf16 v[56:59], v[170:173], v[194:197], v[56:59]
	v_mfma_f32_16x16x32_bf16 v[52:55], v[174:177], v[190:193], v[52:55]
	v_mfma_f32_16x16x32_bf16 v[52:55], v[186:189], v[194:197], v[52:55]
	v_mfma_f32_16x16x32_bf16 v[40:43], v[166:169], v[198:201], v[40:43]
	v_mfma_f32_16x16x32_bf16 v[40:43], v[170:173], v[202:205], v[40:43]
	v_mfma_f32_16x16x32_bf16 v[36:39], v[174:177], v[198:201], v[36:39]
	v_mfma_f32_16x16x32_bf16 v[36:39], v[186:189], v[202:205], v[36:39]
	v_mfma_f32_16x16x32_bf16 v[24:27], v[166:169], v[206:209], v[24:27]
	v_mfma_f32_16x16x32_bf16 v[24:27], v[170:173], v[210:213], v[24:27]
	v_mfma_f32_16x16x32_bf16 v[20:23], v[174:177], v[206:209], v[20:23]
	v_mfma_f32_16x16x32_bf16 v[20:23], v[186:189], v[210:213], v[20:23]
	v_mfma_f32_16x16x32_bf16 v[8:11], v[166:169], v[214:217], v[8:11]
	v_mfma_f32_16x16x32_bf16 v[8:11], v[170:173], v[218:221], v[8:11]
	v_mfma_f32_16x16x32_bf16 v[4:7], v[174:177], v[214:217], v[4:7]
	v_mfma_f32_16x16x32_bf16 v[4:7], v[186:189], v[218:221], v[4:7]
	s_setprio 0
	s_barrier
	s_add_i32 s20, s20, 2
	s_add_u32 s10, s10, 0x100
	s_addc_u32 s11, s11, 0
	s_add_u32 s0, s0, 0x100
	s_addc_u32 s1, s1, 0
	s_cmp_gt_u32 s20, 61
	s_cbranch_scc0 .LBB0_1226
	s_and_b64 vcc, exec, s[48:49]
	s_cbranch_vccz .LBB0_1229
	s_barrier
